# attention fast path for all non-diagonal key tiles: distance bias added by one extra K=8 bf16 MFMA per 32-key tile (exact), per-query shift folded into running max, exp2(fma) in place, permlane32_swap
# speedup vs baseline: 1.0370x; 1.0300x over previous
; DI void attn_item(const Params& p, int l, int item, char* lds) {
;     ...
;   bf16x8 qf[4];
;   {
;     const bf16_t* qp = p.z + (size_t)(qrow0 + qh * 32 + q) * NZ + C_Q + h * 128 + m * 64;
; #pragma unroll
;     for (int ks = 0; ks < 4; ++ks) qf[ks] = *(const bf16x8*)(qp + ks * 16 + hh * 8);
;   }
;   const float slope = exp2f(-2.0f * (float)(h + 1));
;   const float LOG2E = 1.4426950408889634f;
;   const float c1 = 0.125f * LOG2E, sl2 = slope * LOG2E;
;   const float qposf = (float)(qpos0 + qh * 32 + q);
;   f32x16 O[4];
; #pragma unroll
;   for (int i = 0; i < 4; ++i)
; #pragma unroll
;     for (int e = 0; e < 16; ++e) O[i][e] = 0.f;
;   float mrun = -1e30f, lrun = 0.f;
;   u32x4 rk[4], rv[4];
.LBB0_589:
	v_and_b32_e32 v163, 31, v3
	v_lshlrev_b32_e32 v168, 3, v169
	v_mov_b32_e32 v79, 0
	s_andn2_b64 vcc, exec, s[2:3]
	v_mov_b32_e32 v78, 0
	v_mov_b32_e32 v77, 0
	v_mov_b32_e32 v76, 0
	v_mov_b32_e32 v75, 0
	v_mov_b32_e32 v74, 0
	v_mov_b32_e32 v73, 0
	v_mov_b32_e32 v72, 0
	v_mov_b32_e32 v71, 0
	v_mov_b32_e32 v70, 0
	v_mov_b32_e32 v69, 0
	v_mov_b32_e32 v68, 0
	v_mov_b32_e32 v67, 0
	v_mov_b32_e32 v66, 0
	v_mov_b32_e32 v65, 0
	v_mov_b32_e32 v64, 0
	v_mov_b32_e32 v63, 0
	v_mov_b32_e32 v62, 0
	v_mov_b32_e32 v61, 0
	v_mov_b32_e32 v60, 0
	v_mov_b32_e32 v59, 0
	v_mov_b32_e32 v58, 0
	v_mov_b32_e32 v57, 0
	v_mov_b32_e32 v56, 0
	v_mov_b32_e32 v55, 0
	v_mov_b32_e32 v54, 0
	v_mov_b32_e32 v53, 0
	v_mov_b32_e32 v52, 0
	v_mov_b32_e32 v51, 0
	v_mov_b32_e32 v50, 0
	v_mov_b32_e32 v49, 0
	v_mov_b32_e32 v48, 0
	v_mov_b32_e32 v47, 0
	v_mov_b32_e32 v46, 0
	v_mov_b32_e32 v45, 0
	v_mov_b32_e32 v44, 0
	v_mov_b32_e32 v43, 0
	v_mov_b32_e32 v42, 0
	v_mov_b32_e32 v41, 0
	v_mov_b32_e32 v40, 0
	v_mov_b32_e32 v39, 0
	v_mov_b32_e32 v38, 0
	v_mov_b32_e32 v37, 0
	v_mov_b32_e32 v36, 0
	v_mov_b32_e32 v35, 0
	v_mov_b32_e32 v34, 0
	v_mov_b32_e32 v33, 0
	v_mov_b32_e32 v32, 0
	v_mov_b32_e32 v31, 0
	v_mov_b32_e32 v30, 0
	v_mov_b32_e32 v29, 0
	v_mov_b32_e32 v28, 0
	v_mov_b32_e32 v27, 0
	v_mov_b32_e32 v26, 0
	v_mov_b32_e32 v25, 0
	v_mov_b32_e32 v24, 0
	v_mov_b32_e32 v23, 0
	v_mov_b32_e32 v22, 0
	v_mov_b32_e32 v21, 0
	v_mov_b32_e32 v20, 0
	v_mov_b32_e32 v19, 0
	v_mov_b32_e32 v18, 0
	v_mov_b32_e32 v17, 0
	v_mov_b32_e32 v16, 0
	v_mov_b32_e32 v3, 0
	v_mov_b32_e32 v185, v218
	s_cbranch_vccnz .LBB0_607
	s_not_b32 s2, s40
	s_lshl_b32 s2, s2, 1
	v_ldexp_f32 v0, 1.0, s2
	s_add_i32 vcc_lo, s2, 0x82
	s_lshl_b32 vcc_lo, vcc_lo, 7
	s_add_i32 vcc_hi, s2, 0x87
	s_lshl_b32 vcc_hi, vcc_hi, 23
	s_or_b32 vcc_hi, vcc_hi, vcc_lo
	v_cmp_eq_u32_e64 s[2:3], 0, v169
	v_cvt_f32_u32_e32 v205, v163
	v_lshrrev_b32_e32 v205, 16, v205
	v_or_b32_e32 v205, 0x3f800000, v205
	v_mov_b32_e32 v207, 0
	v_mov_b32_e32 v215, 0
	v_mov_b32_e32 v217, 0
	v_cndmask_b32_e64 v206, 0, v205, s[2:3]
	v_mov_b32_e32 v205, vcc_lo
	v_cndmask_b32_e64 v214, 0, v205, s[2:3]
	v_mov_b32_e32 v205, vcc_hi
	s_nop 0
	v_cndmask_b32_e64 v216, 0, v205, s[2:3]
	s_lshl_b32 s2, s38, 9
	s_or_b32 s2, s2, s41
	s_lshl_b32 s30, s38, 6
	s_ashr_i32 s3, s2, 31
	s_addk_i32 s30, 0x4000
	s_lshl_b32 s25, s21, 6
	s_lshl_b32 s40, s38, 12
	s_lshl_b64 s[26:27], s[2:3], 13
	s_mul_hi_i32 s36, s30, 0x3100
	s_mul_i32 s37, s30, 0x3100
	s_lshl_b64 s[30:31], s[2:3], 7
	s_lshl_b32 s38, s38, 10
	v_mul_f32_e32 v189, 0x3fb8aa3b, v0
	v_or_b32_e32 v0, s25, v163
	s_add_u32 s25, s16, s24
	s_addc_u32 s45, s17, 0
	s_add_u32 s50, s12, s26
	s_addc_u32 s51, s13, s27
	s_add_u32 s26, s10, s37
	s_addc_u32 s27, s11, s36
	v_add_u32_e32 v2, s39, v2
	v_mbcnt_hi_u32_b32 v185, -1, v213
	s_add_u32 s26, s26, s24
	v_cvt_f32_i32_e32 v187, v2
	v_and_b32_e32 v2, 64, v185
	s_addc_u32 s27, s27, 0
	v_xor_b32_e32 v181, 32, v185
	v_add_u32_e32 v183, 64, v2
	s_add_u32 s26, s26, 0x1500
	v_cmp_lt_i32_e32 vcc, v181, v183
	s_addc_u32 s27, s27, 0
	v_lshlrev_b32_e32 v16, 1, v168
	v_cndmask_b32_e32 v2, v185, v181, vcc
	s_add_u32 s30, s14, s30
	v_lshlrev_b32_e32 v200, 2, v2
	v_sub_u32_e32 v2, v16, v168
	v_mul_u32_u24_e32 v17, 0x90, v0
	v_mul_u32_u24_e32 v0, 0x48, v163
	s_addc_u32 s31, s15, s31
	s_lshl_b64 s[2:3], s[2:3], 11
	v_readlane_b32 s36, v254, 31
	v_mov_b32_e32 v14, v1
	v_mov_b32_e32 v15, v1
	v_lshl_add_u32 v201, v0, 1, v2
	s_add_u32 s36, s36, s2
	v_readlane_b32 s2, v254, 32
	v_mov_b32_e32 v0, v1
	v_mov_b32_e32 v2, v1
	v_mov_b32_e32 v3, v1
	v_mov_b32_e32 v4, v1
	v_mov_b32_e32 v5, v1
	v_mov_b32_e32 v6, v1
	v_mov_b32_e32 v7, v1
	v_mov_b32_e32 v8, v1
	v_mov_b32_e32 v9, v1
	v_mov_b32_e32 v10, v1
	v_mov_b32_e32 v11, v1
	v_mov_b32_e32 v12, v1
	v_mov_b32_e32 v13, v1
	v_add_u32_e32 v202, v16, v17
	v_mov_b64_e32 v[30:31], v[14:15]
	v_mov_b64_e32 v[46:47], v[14:15]
	v_mov_b64_e32 v[62:63], v[14:15]
	v_mov_b64_e32 v[78:79], v[14:15]
	v_lshlrev_b32_e32 v199, 2, v169
	s_mov_b32 s39, 0
	s_addc_u32 s37, s2, s3
	s_or_b32 s38, s38, 64
	s_or_b32 s92, s40, 64
	v_mov_b32_e32 v204, 0xf149f2ca
	v_mov_b32_e32 v203, 0
	v_mov_b64_e32 v[28:29], v[12:13]
	v_mov_b64_e32 v[26:27], v[10:11]
	v_mov_b64_e32 v[24:25], v[8:9]
	v_mov_b64_e32 v[22:23], v[6:7]
	v_mov_b64_e32 v[20:21], v[4:5]
	v_mov_b64_e32 v[18:19], v[2:3]
	v_mov_b64_e32 v[16:17], v[0:1]
	v_mov_b64_e32 v[44:45], v[12:13]
	v_mov_b64_e32 v[42:43], v[10:11]
	v_mov_b64_e32 v[40:41], v[8:9]
	v_mov_b64_e32 v[38:39], v[6:7]
	v_mov_b64_e32 v[36:37], v[4:5]
	v_mov_b64_e32 v[34:35], v[2:3]
	v_mov_b64_e32 v[32:33], v[0:1]
	v_mov_b64_e32 v[60:61], v[12:13]
	v_mov_b64_e32 v[58:59], v[10:11]
	v_mov_b64_e32 v[56:57], v[8:9]
	v_mov_b64_e32 v[54:55], v[6:7]
	v_mov_b64_e32 v[52:53], v[4:5]
	v_mov_b64_e32 v[50:51], v[2:3]
	v_mov_b64_e32 v[48:49], v[0:1]
	v_mov_b64_e32 v[76:77], v[12:13]
	v_mov_b64_e32 v[74:75], v[10:11]
	v_mov_b64_e32 v[72:73], v[8:9]
	v_mov_b64_e32 v[70:71], v[6:7]
	v_mov_b64_e32 v[68:69], v[4:5]
	v_mov_b64_e32 v[66:67], v[2:3]
	v_mov_b64_e32 v[64:65], v[0:1]

; DI void attn_item(const Params& p, int l, int item, char* lds) {
;     ...
;   auto gload = [&](int j) {
;     const bf16_t* kb; size_t kld; const bf16_t* vb; size_t vld;
;     if (!samp) { kb = p.z + (size_t)(b * 4096 + j * 64) * NZ + C_K + h * 128; kld = NZ; vb = p.vtp + (size_t)((b * 4 + h) * 128) * 4096 + j * 64; vld = 4096; }
;     else if (j < 16) { kb = p.kc + (size_t)(b * 1024 + j * 64) * 512 + h * 128; kld = 512; vb = p.vct + (size_t)((b * 4 + h) * 128) * 1024 + j * 64; vld = 1024; }
;     else { kb = p.z + (size_t)(MP + b * 64) * NZ + C_K + h * 128; kld = NZ; vb = p.vts + (size_t)((b * 4 + h) * 128) * 64; vld = 64; }
; #pragma unroll
;     for (int i = 0; i < 4; ++i) {
;       const int c = tid + 256 * i;
;       const int mm = c >> 9, key = (c >> 3) & 63, d8 = (c & 7) * 8;
;       rk[i] = *(const u32x4*)(kb + (size_t)key * kld + mm * 64 + d8);
;       const int vd = c >> 3, k8 = (c & 7) * 8;
;       rv[i] = *(const u32x4*)(vb + (size_t)vd * vld + k8);
;     }
;   };
;     ...
;     float mx = -1e30f;
;     const float dbase = qposf - (float)(j * 64 + 4 * hh);
; #pragma unroll
;     for (int kt = 0; kt < 2; ++kt)
; #pragma unroll
;       for (int e = 0; e < 16; ++e) {
;         const float dd = dbase - (float)(kt * 32 + (e & 3) + 8 * (e >> 2));
;         const float v = s[kt][e] * c1 - sl2 * fabsf(dd);
;         s[kt][e] = v; mx = fmaxf(mx, v);
;       }
;     mx = fmaxf(mx, __shfl_xor(mx, 32));
;     const float mnew = fmaxf(mrun, mx);
;     const float alpha = __builtin_amdgcn_exp2f(mrun - mnew);
;     const bool resc = mnew > mrun;
;     mrun = mnew;
;     float ps = 0.f;
; #pragma unroll
;     for (int kt = 0; kt < 2; ++kt)
; #pragma unroll
;       for (int e = 0; e < 16; ++e) { const float pe = __builtin_amdgcn_exp2f(s[kt][e] - mnew); s[kt][e] = pe; ps += pe; }
;     lrun = lrun * alpha + ps;
;     if (__any(resc)) {
; #pragma unroll
;       for (int i = 0; i < 4; ++i)
; #pragma unroll
;         for (int e = 0; e < 16; ++e) O[i][e] *= alpha;
;     }
.LBB0_599:
	v_mul_u32_u24_e32 v0, s2, v192
	v_lshlrev_b32_e32 v0, 1, v0
	v_lshl_add_u64 v[2:3], s[42:43], 0, v[0:1]
	v_lshl_add_u64 v[2:3], v[170:171], 1, v[2:3]
	v_mov_b32_e32 v173, v1
	v_lshl_add_u64 v[2:3], v[2:3], 0, v[172:173]
	global_load_dwordx4 v[128:131], v[2:3], off
	v_mad_i64_i32 v[2:3], s[94:95], vcc_lo, v167, 0
	v_lshl_add_u64 v[2:3], v[2:3], 1, s[46:47]
	v_mul_u32_u24_e32 v0, s2, v194
	v_lshl_add_u64 v[2:3], v[2:3], 0, v[172:173]
	v_lshlrev_b32_e32 v0, 1, v0
	global_load_dwordx4 v[132:135], v[2:3], off
	v_lshl_add_u64 v[2:3], s[42:43], 0, v[0:1]
	v_lshl_add_u64 v[2:3], v[174:175], 1, v[2:3]
	v_lshl_add_u64 v[2:3], v[2:3], 0, v[172:173]
	global_load_dwordx4 v[136:139], v[2:3], off
	v_mad_i64_i32 v[2:3], s[94:95], vcc_lo, v193, 0
	v_lshl_add_u64 v[2:3], v[2:3], 1, s[46:47]
	v_mul_u32_u24_e32 v0, s2, v196
	v_lshl_add_u64 v[2:3], v[2:3], 0, v[172:173]
	v_lshlrev_b32_e32 v0, 1, v0
	global_load_dwordx4 v[140:143], v[2:3], off
	v_lshl_add_u64 v[2:3], s[42:43], 0, v[0:1]
	v_lshl_add_u64 v[2:3], v[176:177], 1, v[2:3]
	v_lshl_add_u64 v[2:3], v[2:3], 0, v[172:173]
	global_load_dwordx4 v[144:147], v[2:3], off
	v_mad_i64_i32 v[2:3], s[94:95], vcc_lo, v195, 0
	v_lshl_add_u64 v[2:3], v[2:3], 1, s[46:47]
	v_mul_u32_u24_e32 v0, s2, v198
	v_lshl_add_u64 v[2:3], v[2:3], 0, v[172:173]
	v_lshlrev_b32_e32 v0, 1, v0
	global_load_dwordx4 v[148:151], v[2:3], off
	v_lshl_add_u64 v[2:3], s[42:43], 0, v[0:1]
	v_lshl_add_u64 v[2:3], v[178:179], 1, v[2:3]
	v_lshl_add_u64 v[2:3], v[2:3], 0, v[172:173]
	global_load_dwordx4 v[152:155], v[2:3], off
	v_mad_i64_i32 v[2:3], s[2:3], vcc_lo, v197, 0
	v_lshl_add_u64 v[2:3], v[2:3], 1, s[46:47]
	v_lshl_add_u64 v[2:3], v[2:3], 0, v[172:173]
	global_load_dwordx4 v[156:159], v[2:3], off
	s_movk_i32 s94, 0x3100
	s_movk_i32 s95, 0x50
	s_branch .Lfa_body
.Lfa_body:
	ds_read_b128 v[2:5], v202
	ds_read_b128 v[6:9], v202 offset:32
	ds_read_b128 v[10:13], v202 offset:64
	ds_read_b128 v[222:225], v202 offset:96
	ds_read_b128 v[226:229], v202 offset:4608
	v_mfma_f32_32x32x8_bf16 v[96:111], v[206:207], v[214:215], 0
	v_mfma_f32_32x32x8_bf16 v[80:95], v[206:207], v[216:217], 0
	s_waitcnt lgkmcnt(4)
	v_mfma_f32_32x32x16_bf16 v[96:111], v[2:5], v[120:123], v[96:111]
	ds_read_b128 v[2:5], v202 offset:4640
	s_waitcnt lgkmcnt(4)
	v_mfma_f32_32x32x16_bf16 v[96:111], v[6:9], v[112:115], v[96:111]
	ds_read_b128 v[6:9], v202 offset:4672
	s_waitcnt lgkmcnt(4)
	v_mfma_f32_32x32x16_bf16 v[96:111], v[10:13], v[116:119], v[96:111]
	ds_read_b128 v[10:13], v202 offset:4704
	s_waitcnt lgkmcnt(4)
	v_mfma_f32_32x32x16_bf16 v[96:111], v[222:225], v[124:127], v[96:111]
	s_waitcnt lgkmcnt(3)
	v_mfma_f32_32x32x16_bf16 v[80:95], v[226:229], v[120:123], v[80:95]
	s_waitcnt lgkmcnt(2)
	v_mfma_f32_32x32x16_bf16 v[80:95], v[2:5], v[112:115], v[80:95]
	s_waitcnt lgkmcnt(1)
	v_mfma_f32_32x32x16_bf16 v[80:95], v[6:9], v[116:119], v[80:95]
	s_waitcnt lgkmcnt(0)
	v_mfma_f32_32x32x16_bf16 v[80:95], v[10:13], v[124:127], v[80:95]
	v_add_u32_e32 v161, 0x4800, v201
	v_add_u32_e32 v173, 0x5800, v201
	v_add_u32_e32 v188, 0x6800, v201
	v_add_u32_e32 v208, 0x7800, v201
	ds_read2_b64 v[222:225], v208 offset0:192 offset1:194
	ds_read2_b64 v[226:229], v161 offset0:4 offset1:6
	s_lshl_b32 s2, s93, 6
	s_sub_i32 s2, s2, 64
	v_cvt_f32_u32_e32 v14, s2
	v_sub_f32_e32 v14, v187, v14
	v_mul_f32_e32 v14, v189, v14
	ds_read2_b64 v[2:5], v161 offset1:2
	ds_read2_b64 v[6:9], v173 offset0:64 offset1:66
	ds_read2_b64 v[10:13], v188 offset0:128 offset1:130
	v_max3_f32 v0, v96, v97, v98
	v_max3_f32 v0, v0, v99, v100
	v_max3_f32 v0, v0, v101, v102
	v_max3_f32 v0, v0, v103, v104
	v_max3_f32 v0, v0, v105, v106
	v_max3_f32 v0, v0, v107, v108
	v_max3_f32 v0, v0, v109, v110
	v_max_f32_e32 v0, v0, v111
	v_max3_f32 v15, v80, v81, v82
	v_max3_f32 v15, v15, v83, v84
	v_max3_f32 v15, v15, v85, v86
	v_max3_f32 v15, v15, v87, v88
	v_max3_f32 v15, v15, v89, v90
	v_max3_f32 v15, v15, v91, v92
	v_max3_f32 v15, v15, v93, v94
	v_max_f32_e32 v15, v15, v95
	v_max_f32_e32 v0, v0, v15
	v_mov_b32_e32 v15, v0
	s_nop 1
	v_permlane32_swap_b32_e32 v15, v0
	s_nop 1
	v_max_f32_e32 v0, v0, v15
	v_fma_f32 v0, v0, s35, -v14
	v_sub_f32_e32 v15, v0, v204
	v_cmp_lt_f32_e32 vcc, 0x41000000, v15
	s_nop 1
	v_cndmask_b32_e32 v15, v204, v0, vcc
	v_sub_f32_e32 v0, v204, v15
	v_exp_f32_e32 v0, v0
	v_mov_b32_e32 v204, v15
	v_add_f32_e32 v14, v15, v14
	s_cbranch_vccz .Lfa_keep
	v_pk_mul_f32 v[78:79], v[78:79], v[0:1] op_sel_hi:[1,0]
	v_pk_mul_f32 v[76:77], v[76:77], v[0:1] op_sel_hi:[1,0]
	v_pk_mul_f32 v[74:75], v[74:75], v[0:1] op_sel_hi:[1,0]
	v_pk_mul_f32 v[72:73], v[72:73], v[0:1] op_sel_hi:[1,0]
	v_pk_mul_f32 v[70:71], v[70:71], v[0:1] op_sel_hi:[1,0]
	v_pk_mul_f32 v[68:69], v[68:69], v[0:1] op_sel_hi:[1,0]
	v_pk_mul_f32 v[66:67], v[66:67], v[0:1] op_sel_hi:[1,0]
	v_pk_mul_f32 v[64:65], v[64:65], v[0:1] op_sel_hi:[1,0]
	v_pk_mul_f32 v[62:63], v[62:63], v[0:1] op_sel_hi:[1,0]
	v_pk_mul_f32 v[60:61], v[60:61], v[0:1] op_sel_hi:[1,0]
	v_pk_mul_f32 v[58:59], v[58:59], v[0:1] op_sel_hi:[1,0]
	v_pk_mul_f32 v[56:57], v[56:57], v[0:1] op_sel_hi:[1,0]
	v_pk_mul_f32 v[54:55], v[54:55], v[0:1] op_sel_hi:[1,0]
	v_pk_mul_f32 v[52:53], v[52:53], v[0:1] op_sel_hi:[1,0]
	v_pk_mul_f32 v[50:51], v[50:51], v[0:1] op_sel_hi:[1,0]
	v_pk_mul_f32 v[48:49], v[48:49], v[0:1] op_sel_hi:[1,0]
	v_pk_mul_f32 v[46:47], v[46:47], v[0:1] op_sel_hi:[1,0]
	v_pk_mul_f32 v[44:45], v[44:45], v[0:1] op_sel_hi:[1,0]
	v_pk_mul_f32 v[42:43], v[42:43], v[0:1] op_sel_hi:[1,0]
	v_pk_mul_f32 v[40:41], v[40:41], v[0:1] op_sel_hi:[1,0]
	v_pk_mul_f32 v[38:39], v[38:39], v[0:1] op_sel_hi:[1,0]
	v_pk_mul_f32 v[36:37], v[36:37], v[0:1] op_sel_hi:[1,0]
	v_pk_mul_f32 v[34:35], v[34:35], v[0:1] op_sel_hi:[1,0]
	v_pk_mul_f32 v[32:33], v[32:33], v[0:1] op_sel_hi:[1,0]
	v_pk_mul_f32 v[30:31], v[30:31], v[0:1] op_sel_hi:[1,0]
	v_pk_mul_f32 v[28:29], v[28:29], v[0:1] op_sel_hi:[1,0]
	v_pk_mul_f32 v[26:27], v[26:27], v[0:1] op_sel_hi:[1,0]
	v_pk_mul_f32 v[24:25], v[24:25], v[0:1] op_sel_hi:[1,0]
	v_pk_mul_f32 v[22:23], v[22:23], v[0:1] op_sel_hi:[1,0]
	v_pk_mul_f32 v[20:21], v[20:21], v[0:1] op_sel_hi:[1,0]
	v_pk_mul_f32 v[18:19], v[18:19], v[0:1] op_sel_hi:[1,0]
	v_pk_mul_f32 v[16:17], v[16:17], v[0:1] op_sel_hi:[1,0]
; DI unsigned pk2(float a, float b) { f32x2 v = {a, b}; bfv2 r = __builtin_convertvector(v, bfv2); return __builtin_bit_cast(unsigned, r); }
; DI void attn_item(const Params& p, int l, int item, char* lds) {
;     ...
; #pragma unroll
;     for (int kt = 0; kt < 2; ++kt)
; #pragma unroll
;       for (int e = 0; e < 16; ++e) { const float pe = __builtin_amdgcn_exp2f(s[kt][e] - mnew); s[kt][e] = pe; ps += pe; }
;     lrun = lrun * alpha + ps;
;     if (__any(resc)) {
; #pragma unroll
;       for (int i = 0; i < 4; ++i)
; #pragma unroll
;         for (int e = 0; e < 16; ++e) O[i][e] *= alpha;
;     }
; #pragma unroll
;     for (int kt = 0; kt < 2; ++kt)
; #pragma unroll
;       for (int sx = 0; sx < 2; ++sx) {
;         u32x4 pb;
;         pb[0] = pk2(s[kt][8 * sx + 0], s[kt][8 * sx + 1]); pb[1] = pk2(s[kt][8 * sx + 2], s[kt][8 * sx + 3]);
;         pb[2] = pk2(s[kt][8 * sx + 4], s[kt][8 * sx + 5]); pb[3] = pk2(s[kt][8 * sx + 6], s[kt][8 * sx + 7]);
;         const bf16x8 pf = __builtin_bit_cast(bf16x8, pb);
; #pragma unroll
;         for (int vt = 0; vt < 4; ++vt) {
;           const bf16_t* vp = Vs + (vt * 32 + q) * ALD + kt * 32 + 16 * sx + 4 * hh;
;           const s16x4 lo = *(const s16x4*)vp, hi = *(const s16x4*)(vp + 8);
;           const bf16x8 vf = __builtin_shufflevector(lo, hi, 0, 1, 2, 3, 4, 5, 6, 7);
;           O[vt] = __builtin_amdgcn_mfma_f32_32x32x16_bf16(vf, pf, O[vt], 0, 0, 0);
;         }
;       }
;     __syncthreads();
;     if (j + 1 < nch) sstore();
;     __syncthreads();
.Lfa_keep:
	v_fma_f32 v96, v96, s35, -v14
	v_fma_f32 v97, v97, s35, -v14
	v_fma_f32 v98, v98, s35, -v14
	v_fma_f32 v99, v99, s35, -v14
	v_fma_f32 v100, v100, s35, -v14
	v_fma_f32 v101, v101, s35, -v14
	v_fma_f32 v102, v102, s35, -v14
	v_fma_f32 v103, v103, s35, -v14
	v_exp_f32_e32 v96, v96
	v_exp_f32_e32 v97, v97
	v_exp_f32_e32 v98, v98
	v_exp_f32_e32 v99, v99
	v_exp_f32_e32 v100, v100
	v_exp_f32_e32 v101, v101
	v_exp_f32_e32 v102, v102
	v_exp_f32_e32 v103, v103
	v_mov_b32_e32 v15, v96
	v_mov_b32_e32 v205, v97
	v_add_f32_e32 v15, v15, v98
	v_add_f32_e32 v205, v205, v99
	v_add_f32_e32 v15, v15, v100
	v_add_f32_e32 v205, v205, v101
	v_add_f32_e32 v15, v15, v102
	v_add_f32_e32 v205, v205, v103
	v_cvt_pk_bf16_f32 v96, v96, v97
	v_cvt_pk_bf16_f32 v97, v98, v99
	v_cvt_pk_bf16_f32 v98, v100, v101
	v_cvt_pk_bf16_f32 v99, v102, v103
	v_fma_f32 v104, v104, s35, -v14
	v_fma_f32 v105, v105, s35, -v14
	s_waitcnt lgkmcnt(2)
	v_mfma_f32_32x32x16_bf16 v[64:79], v[2:5], v[96:99], v[64:79]
	ds_read2_b64 v[2:5], v173 offset0:68 offset1:70
	v_fma_f32 v106, v106, s35, -v14
	v_fma_f32 v107, v107, s35, -v14
	v_fma_f32 v108, v108, s35, -v14
	v_fma_f32 v109, v109, s35, -v14
	v_fma_f32 v110, v110, s35, -v14
	v_fma_f32 v111, v111, s35, -v14
	v_exp_f32_e32 v104, v104
	s_waitcnt lgkmcnt(2)
	v_mfma_f32_32x32x16_bf16 v[48:63], v[6:9], v[96:99], v[48:63]
	ds_read2_b64 v[6:9], v188 offset0:132 offset1:134
	v_exp_f32_e32 v105, v105
	v_exp_f32_e32 v106, v106
	v_exp_f32_e32 v107, v107
	v_exp_f32_e32 v108, v108
	v_exp_f32_e32 v109, v109
	v_exp_f32_e32 v110, v110
	v_exp_f32_e32 v111, v111
	s_waitcnt lgkmcnt(2)
	v_mfma_f32_32x32x16_bf16 v[32:47], v[10:13], v[96:99], v[32:47]
	ds_read2_b64 v[10:13], v208 offset0:196 offset1:198
	v_add_f32_e32 v15, v15, v104
	v_add_f32_e32 v205, v205, v105
	v_add_f32_e32 v15, v15, v106
	v_add_f32_e32 v205, v205, v107
	v_add_f32_e32 v15, v15, v108
	v_add_f32_e32 v205, v205, v109
	v_add_f32_e32 v15, v15, v110
	s_waitcnt lgkmcnt(7)
	v_mfma_f32_32x32x16_bf16 v[16:31], v[222:225], v[96:99], v[16:31]
	ds_read2_b64 v[222:225], v161 offset0:8 offset1:10
	v_add_f32_e32 v205, v205, v111
	v_cvt_pk_bf16_f32 v104, v104, v105
	v_cvt_pk_bf16_f32 v105, v106, v107
	v_cvt_pk_bf16_f32 v106, v108, v109
	v_cvt_pk_bf16_f32 v107, v110, v111
	v_fma_f32 v80, v80, s35, -v14
	v_fma_f32 v81, v81, s35, -v14
	s_waitcnt lgkmcnt(7)
	v_mfma_f32_32x32x16_bf16 v[64:79], v[226:229], v[104:107], v[64:79]
	ds_read2_b64 v[226:229], v173 offset0:72 offset1:74
	v_fma_f32 v82, v82, s35, -v14
	v_fma_f32 v83, v83, s35, -v14
	v_fma_f32 v84, v84, s35, -v14
	v_fma_f32 v85, v85, s35, -v14
	v_fma_f32 v86, v86, s35, -v14
	v_fma_f32 v87, v87, s35, -v14
	v_exp_f32_e32 v80, v80
	s_waitcnt lgkmcnt(4)
	v_mfma_f32_32x32x16_bf16 v[48:63], v[2:5], v[104:107], v[48:63]
	ds_read2_b64 v[2:5], v188 offset0:136 offset1:138
	v_exp_f32_e32 v81, v81
	v_exp_f32_e32 v82, v82
	v_exp_f32_e32 v83, v83
	v_exp_f32_e32 v84, v84
	v_exp_f32_e32 v85, v85
	v_exp_f32_e32 v86, v86
	v_exp_f32_e32 v87, v87
	s_waitcnt lgkmcnt(4)
	v_mfma_f32_32x32x16_bf16 v[32:47], v[6:9], v[104:107], v[32:47]
	ds_read2_b64 v[6:9], v208 offset0:200 offset1:202
	v_add_f32_e32 v15, v15, v80
	v_add_f32_e32 v205, v205, v81
	v_add_f32_e32 v15, v15, v82
	v_add_f32_e32 v205, v205, v83
	v_add_f32_e32 v15, v15, v84
	v_add_f32_e32 v205, v205, v85
	v_add_f32_e32 v15, v15, v86
	s_waitcnt lgkmcnt(4)
	v_mfma_f32_32x32x16_bf16 v[16:31], v[10:13], v[104:107], v[16:31]
	ds_read2_b64 v[10:13], v161 offset0:12 offset1:14
	v_add_f32_e32 v205, v205, v87
	v_cvt_pk_bf16_f32 v80, v80, v81
	v_cvt_pk_bf16_f32 v81, v82, v83
	v_cvt_pk_bf16_f32 v82, v84, v85
	v_cvt_pk_bf16_f32 v83, v86, v87
	v_fma_f32 v88, v88, s35, -v14
	v_fma_f32 v89, v89, s35, -v14
	s_waitcnt lgkmcnt(4)
	v_mfma_f32_32x32x16_bf16 v[64:79], v[222:225], v[80:83], v[64:79]
	ds_read2_b64 v[222:225], v173 offset0:76 offset1:78
	v_fma_f32 v90, v90, s35, -v14
	v_fma_f32 v91, v91, s35, -v14
	v_fma_f32 v92, v92, s35, -v14
	v_fma_f32 v93, v93, s35, -v14
	v_fma_f32 v94, v94, s35, -v14
	v_fma_f32 v95, v95, s35, -v14
	v_exp_f32_e32 v88, v88
	s_waitcnt lgkmcnt(4)
	v_mfma_f32_32x32x16_bf16 v[48:63], v[226:229], v[80:83], v[48:63]
	ds_read2_b64 v[226:229], v188 offset0:140 offset1:142
	v_exp_f32_e32 v89, v89
	v_exp_f32_e32 v90, v90
	v_exp_f32_e32 v91, v91
	v_exp_f32_e32 v92, v92
	v_exp_f32_e32 v93, v93
	v_exp_f32_e32 v94, v94
	v_exp_f32_e32 v95, v95
	s_waitcnt lgkmcnt(4)
	v_mfma_f32_32x32x16_bf16 v[32:47], v[2:5], v[80:83], v[32:47]
	ds_read2_b64 v[2:5], v208 offset0:204 offset1:206
	v_add_f32_e32 v15, v15, v88
	v_add_f32_e32 v205, v205, v89
	v_add_f32_e32 v15, v15, v90
	v_add_f32_e32 v205, v205, v91
	v_add_f32_e32 v15, v15, v92
	v_add_f32_e32 v205, v205, v93
	v_add_f32_e32 v15, v15, v94
	s_waitcnt lgkmcnt(4)
	v_mfma_f32_32x32x16_bf16 v[16:31], v[6:9], v[80:83], v[16:31]
	v_add_f32_e32 v205, v205, v95
	v_cvt_pk_bf16_f32 v88, v88, v89
	v_cvt_pk_bf16_f32 v89, v90, v91
	v_cvt_pk_bf16_f32 v90, v92, v93
	v_cvt_pk_bf16_f32 v91, v94, v95
	s_waitcnt lgkmcnt(0)
	s_barrier
	s_nop 1
	v_mfma_f32_32x32x16_bf16 v[64:79], v[10:13], v[88:91], v[64:79]
	s_waitcnt vmcnt(7)
	ds_write_b128 v180, v[128:131]
	s_waitcnt vmcnt(6)
	ds_write_b128 v180, v[132:135] offset:18432
	v_mfma_f32_32x32x16_bf16 v[48:63], v[222:225], v[88:91], v[48:63]
	s_waitcnt vmcnt(5)
	ds_write_b128 v182, v[136:139]
	s_waitcnt vmcnt(4)
	ds_write_b128 v182, v[140:143] offset:18432
	v_mfma_f32_32x32x16_bf16 v[32:47], v[226:229], v[88:91], v[32:47]
	s_waitcnt vmcnt(3)
	ds_write_b128 v184, v[144:147]
	s_waitcnt vmcnt(2)
	ds_write_b128 v184, v[148:151] offset:18432
	v_mfma_f32_32x32x16_bf16 v[16:31], v[2:5], v[88:91], v[16:31]
	s_waitcnt vmcnt(1)
	ds_write_b128 v186, v[152:155]
	s_waitcnt vmcnt(0)
	ds_write_b128 v186, v[156:159] offset:18432
	v_add_f32_e32 v15, v15, v205
	s_add_u32 s36, s36, 0x80
	s_addc_u32 s37, s37, 0
	s_add_i32 s38, s38, 64
	s_add_i32 s92, s92, 64
	v_fma_f32 v203, v203, v0, v15
	v_add_u32_e32 v199, 64, v199
	s_mov_b32 s39, s93
	s_waitcnt lgkmcnt(0)
	s_barrier
	s_branch .LBB0_591
